# stack + the sample item's idle waves 2-7 touch the following prompt item's K/V/Q/z lines (L2 warm-up) while waves 0-1 run the sample attention
# baseline (speedup 1.0000x reference)
; #define LAS __attribute__((address_space(3)))
; template <bool SAMPLE>
; __device__ __forceinline__ void attn_prefetch(const bf16_t* __restrict__ proj, int row0, int head0, int lane, u32x4 (&qw)[4], u32x4 (&zw)[4]) {
;     const int r32 = lane & 31, hi = lane >> 5;
;     const int myrow = SAMPLE ? row0 + (r32 & 7) : row0 + r32;
;     const int myhead = SAMPLE ? head0 + (r32 >> 3) : head0;
;     const bf16_t* qp = proj + (size_t)myrow * PO2 + C_Q + myhead * 64 + hi * 8;
; #pragma unroll
;     for (int d0 = 0; d0 < 4; ++d0) qw[d0] = *(const u32x4*)(qp + d0 * 16);
; #pragma unroll
;     for (int it4 = 0; it4 < 4; ++it4) {
;         const int qq = it4 * 8 + (lane >> 3), ch = lane & 7;
;         const int orow = SAMPLE ? row0 + (qq & 7) : row0 + qq;
;         const int ohead = SAMPLE ? head0 + (qq >> 3) : head0;
;         zw[it4] = *(const u32x4*)(proj + (size_t)orow * PO2 + C_ZA + ohead * 64 + ch * 8);
;     }
; __device__ __forceinline__ void attn_prompt_item(const Args& a, int l, int item, LAS unsigned char* lds, int tid, int lane, int wave) {
;     const int kvh = item & 1, b = (item >> 1) & 31, n = item >> 6;
;     const bf16_t* proj = (const bf16_t*)(a.ws + WS_PROJ); bf16_t* Y = (bf16_t*)(a.ws + WS_H);
;     const float* tab = (const float*)(a.ws + WS_ROPE);
;     const float* kg = a.in[13] + l * 64; const float* qg = a.in[12] + l * 64; const float* sinks = a.in[14] + l * 8;
;     LAS unsigned char* Kl = lds; LAS unsigned char* Vl = lds + 36864; LAS float* wsf = (LAS float*)(lds + 36864 + 32768) + wave * 64; LAS bf16_t* ost = (LAS bf16_t*)(lds + 73728 + wave * 4096);
;     const int headw = kvh * 4 + (wave >> 1), qt0 = (wave & 1) * 2, rowq0 = n * LP + b * 128 + qt0 * 32;
;     u32x4 qw0[4], zw0[4], qw1[4], zw1[4];
;     attn_prefetch<false>(proj, rowq0, headw, lane, qw0, zw0); attn_prefetch<false>(proj, rowq0 + 32, headw, lane, qw1, zw1);
;     const int sub = tid & 7, rl = tid >> 3;
;     u32x4 kws[4], vws[4];
; #pragma unroll
;     for (int pass = 0; pass < 4; ++pass) {
;         const int j = pass * 64 + rl; const int pos = 128 * (b - 1) + j; const int posc = pos < 0 ? 0 : pos;
;         const size_t row = (size_t)n * LP + posc;
;         kws[pass] = *(const u32x4*)(proj + row * PO2 + C_K + kvh * 64 + sub * 8);
;         vws[pass] = *(const u32x4*)(proj + row * PO2 + C_V + kvh * 64 + sub * 8);
;     }
.Lppw_warm:
	s_cmp_lg_u32 s42, 0x100
	s_cbranch_scc1 .LBB0_531
	s_and_b32 s0, s71, 1
	s_bfe_u32 s1, s71, 0x50001
	s_lshr_b32 s2, s71, 6
	s_lshl_b32 s2, s2, 12
	v_readfirstlane_b32 s3, v208
	s_lshr_b32 s3, s3, 6
	s_cmp_lt_u32 s3, 4
	s_cbranch_scc0 .Lppw_qz
	s_lshl_b32 s4, s1, 7
	s_addk_i32 s4, 0xff80
	s_lshl_b32 s5, s0, 7
	s_addk_i32 s5, 0xc00
	v_subrev_u32_e32 v228, 0x80, v208
	v_add_u32_e32 v228, s4, v228
	v_add_u32_e32 v229, 0x80, v228
	v_max_i32_e32 v228, 0, v228
	v_max_i32_e32 v229, 0, v229
	v_add_u32_e32 v228, s2, v228
	v_add_u32_e32 v229, s2, v229
	v_mul_u32_u24_e32 v228, 0x1200, v228
	v_mul_u32_u24_e32 v229, 0x1200, v229
	v_add_u32_e32 v228, s5, v228
	v_add_u32_e32 v229, s5, v229
	global_load_dword v227, v228, s[74:75]
	global_load_dword v227, v228, s[74:75] offset:256
	global_load_dword v227, v229, s[74:75]
	global_load_dword v227, v229, s[74:75] offset:256
	s_branch .LBB0_531
.Lppw_qz:
	s_lshl_b32 s4, s1, 7
	s_add_i32 s4, s4, s2
	s_lshl_b32 s5, s0, 9
	v_subrev_u32_e32 v228, 0x100, v208
	v_and_b32_e32 v229, 1, v228
	v_lshrrev_b32_e32 v228, 1, v228
	v_add_u32_e32 v228, s4, v228
	v_mul_u32_u24_e32 v228, 0x1200, v228
	v_mul_u32_u24_e32 v229, 0x600, v229
	v_add3_u32 v228, v228, v229, s5
	global_load_dword v227, v228, s[74:75] offset:2048
	global_load_dword v227, v228, s[74:75] offset:2176
	global_load_dword v227, v228, s[74:75] offset:2304
	global_load_dword v227, v228, s[74:75] offset:2432
	s_branch .LBB0_531
